# attention staging: three vmcnt waits merged into one vmcnt(3), no-op s_add removed (on top of v18)
# baseline (speedup 1.0000x reference)
.Latt_prio_done:
.LBB0_674:
	s_add_i32 s2, s67, -1
	s_and_b32 s2, s2, 3
	s_mulk_i32 s2, 0x3400
	s_and_b32 s71, s67, 2
	s_xor_b32 s3, s71, 2
	v_add_u32_e32 v0, s2, v192
	s_mulk_i32 s3, 0x2400
	s_waitcnt vmcnt(3)
	ds_write_b128 v0, v[152:155]
	v_add_u32_e32 v0, s2, v185
	s_add_i32 s2, s67, 5
	ds_write_b128 v0, v[156:159] offset:128
	v_add_u32_e32 v0, s3, v193
	s_min_i32 s46, s2, s66
	s_add_i32 s2, s67, 4
	v_add_u32_e32 v0, 0xd000, v0
	s_min_i32 s2, s2, s66
	s_lshl_b64 s[4:5], s[46:47], 16
	s_mov_b32 s3, s47
	ds_write2_b64 v0, v[172:173], v[174:175] offset1:2
	v_lshl_add_u64 v[2:3], v[186:187], 0, s[4:5]
	s_lshl_b64 s[4:5], s[46:47], 12
	s_lshl_b64 s[2:3], s[2:3], 7
	v_lshl_add_u64 v[4:5], v[188:189], 0, s[4:5]
	global_load_dwordx4 v[152:155], v[2:3], off
	global_load_dwordx4 v[156:159], v[4:5], off
	v_lshl_add_u64 v[2:3], v[190:191], 0, s[2:3]
	global_load_dwordx4 v[172:175], v[2:3], off
	s_add_i32 s70, s67, 1
	s_and_b32 s69, s70, 3
	s_cmp_gt_i32 s67, s65
	s_cbranch_scc1 .LBB0_685
	s_mul_i32 s2, s69, 0x3400
	v_add_u32_e32 v0, s2, v196
	ds_read_b128 v[2:5], v0
	ds_read_b128 v[6:9], v0 offset:6656
	s_waitcnt lgkmcnt(1)
	v_mfma_f32_32x32x16_bf16 v[112:127], v[2:5], v[128:131], v[48:63]
	ds_read_b128 v[10:13], v0 offset:32
	ds_read_b128 v[202:205], v0 offset:6688
	v_add_f32_e32 v14, 0, v80
	v_add_f32_e32 v14, v81, v14
	v_cvt_pk_bf16_f32 v176, v80, v81
	s_waitcnt lgkmcnt(2)
	v_mfma_f32_32x32x16_bf16 v[96:111], v[6:9], v[128:131], v[48:63]
	v_add_f32_e32 v2, v82, v14
	v_add_f32_e32 v2, v83, v2
	v_add_f32_e32 v14, v84, v2
	v_cvt_pk_bf16_f32 v177, v82, v83
	s_waitcnt lgkmcnt(1)
	v_mfma_f32_32x32x16_bf16 v[112:127], v[10:13], v[132:135], v[112:127]
	ds_read_b128 v[2:5], v0 offset:64
	ds_read_b128 v[6:9], v0 offset:6720
	v_add_f32_e32 v14, v85, v14
	v_add_f32_e32 v14, v86, v14
	v_add_f32_e32 v14, v87, v14
	v_cvt_pk_bf16_f32 v178, v84, v85
	v_cvt_pk_bf16_f32 v179, v86, v87
	s_waitcnt lgkmcnt(2)
	v_mfma_f32_32x32x16_bf16 v[96:111], v[202:205], v[132:135], v[96:111]
	v_add_f32_e32 v10, v88, v14
	v_add_f32_e32 v11, v89, v10
	v_cvt_pk_bf16_f32 v10, v88, v89
	s_waitcnt lgkmcnt(1)
	v_mfma_f32_32x32x16_bf16 v[112:127], v[2:5], v[136:139], v[112:127]
	ds_read_b128 v[80:83], v0 offset:96
	ds_read_b128 v[202:205], v0 offset:6752
	v_add_f32_e32 v11, v90, v11
	v_add_f32_e32 v11, v91, v11
	v_add_f32_e32 v12, v92, v11
	v_cvt_pk_bf16_f32 v11, v90, v91
	s_waitcnt lgkmcnt(2)
	v_mfma_f32_32x32x16_bf16 v[96:111], v[6:9], v[136:139], v[96:111]
	v_add_f32_e32 v2, v93, v12
	v_add_f32_e32 v2, v94, v2
	v_add_f32_e32 v14, v95, v2
	v_cvt_pk_bf16_f32 v12, v92, v93
	v_cvt_pk_bf16_f32 v13, v94, v95
	s_waitcnt lgkmcnt(1)
	v_mfma_f32_32x32x16_bf16 v[112:127], v[80:83], v[140:143], v[112:127]
	ds_read_b128 v[2:5], v0 offset:128
	ds_read_b128 v[206:209], v0 offset:6784
	v_add_f32_e32 v6, v16, v14
	v_add_f32_e32 v7, v17, v6
	v_cvt_pk_bf16_f32 v6, v16, v17
	s_waitcnt lgkmcnt(2)
	v_mfma_f32_32x32x16_bf16 v[96:111], v[202:205], v[140:143], v[96:111]
	v_add_f32_e32 v7, v18, v7
	v_add_f32_e32 v7, v19, v7
	v_add_f32_e32 v8, v20, v7
	v_cvt_pk_bf16_f32 v7, v18, v19
	s_waitcnt lgkmcnt(1)
	v_mfma_f32_32x32x16_bf16 v[112:127], v[2:5], v[144:147], v[112:127]
	ds_read_b128 v[14:17], v0 offset:160
	ds_read_b128 v[80:83], v0 offset:6816
	v_add_f32_e32 v0, v21, v8
	v_add_f32_e32 v0, v22, v0
	v_add_f32_e32 v0, v23, v0
	v_cvt_pk_bf16_f32 v8, v20, v21
	v_cvt_pk_bf16_f32 v9, v22, v23
	s_waitcnt lgkmcnt(2)
	v_mfma_f32_32x32x16_bf16 v[96:111], v[206:209], v[144:147], v[96:111]
	v_add_f32_e32 v0, v24, v0
	v_add_f32_e32 v0, v25, v0
	v_cvt_pk_bf16_f32 v2, v24, v25
	s_waitcnt lgkmcnt(1)
	v_mfma_f32_32x32x16_bf16 v[112:127], v[14:17], v[148:151], v[112:127]
	v_add_f32_e32 v0, v26, v0
	v_add_f32_e32 v0, v27, v0
	v_add_f32_e32 v0, v28, v0
	v_cvt_pk_bf16_f32 v3, v26, v27
	s_waitcnt lgkmcnt(0)
	v_mfma_f32_32x32x16_bf16 v[96:111], v[80:83], v[148:151], v[96:111]
	v_add_f32_e32 v0, v29, v0
	v_add_f32_e32 v0, v30, v0
	v_add_f32_e32 v0, v31, v0
	v_cvt_pk_bf16_f32 v4, v28, v29
	v_cvt_pk_bf16_f32 v5, v30, v31
	s_mul_i32 s4, s71, 0x2400
	v_add_u32_e32 v206, s4, v200
	ds_read_b128 v[16:19], v206 offset:53248
	ds_read_b128 v[202:205], v206 offset:57856
	s_cmp_ge_i32 s67, s65
	v_add_f32_e32 v201, v201, v0
	s_cbranch_scc1 .LBB0_682
	s_sub_i32 s2, s68, 64
	s_cmp_le_i32 s2, s63
	s_cbranch_scc0 .Latt_mask0

.LBB0_685:
	s_mulk_i32 s71, 0x3400
	s_add_i32 s3, s71, 0
	s_xor_b32 s2, s69, 2
	v_add_u32_e32 v0, s3, v192
	s_mulk_i32 s2, 0x2400
	s_waitcnt vmcnt(3)
	ds_write_b128 v0, v[168:171]
	v_add_u32_e32 v0, s3, v185
	ds_write_b128 v0, v[164:167] offset:128
	v_add_u32_e32 v0, s2, v193
	s_add_i32 s2, s67, 6
	s_min_i32 s2, s2, s66
	s_mov_b32 s3, s47
	v_add_u32_e32 v0, 0xd000, v0
	s_lshl_b64 s[4:5], s[2:3], 16
	s_lshl_b64 s[2:3], s[2:3], 12
	ds_write2_b64 v0, v[160:161], v[162:163] offset1:2
	v_lshl_add_u64 v[2:3], v[186:187], 0, s[4:5]
	v_lshl_add_u64 v[4:5], v[188:189], 0, s[2:3]
	s_lshl_b64 s[2:3], s[46:47], 7
	global_load_dwordx4 v[168:171], v[2:3], off
	global_load_dwordx4 v[164:167], v[4:5], off
	v_lshl_add_u64 v[2:3], v[190:191], 0, s[2:3]
	global_load_dwordx4 v[160:163], v[2:3], off
	s_add_i32 s46, s67, 2
	s_cmp_ge_i32 s67, s65
	s_cbranch_scc1 .LBB0_696
	s_and_b32 s2, s46, 2
	s_mulk_i32 s2, 0x3400
	v_add_u32_e32 v0, s2, v196
	ds_read_b128 v[2:5], v0
	ds_read_b128 v[6:9], v0 offset:6656
	s_waitcnt lgkmcnt(1)
	v_mfma_f32_32x32x16_bf16 v[112:127], v[2:5], v[128:131], v[48:63]
	ds_read_b128 v[10:13], v0 offset:32
	ds_read_b128 v[202:205], v0 offset:6688
	v_add_f32_e32 v14, 0, v80
	v_add_f32_e32 v14, v81, v14
	v_cvt_pk_bf16_f32 v176, v80, v81
	s_waitcnt lgkmcnt(2)
	v_mfma_f32_32x32x16_bf16 v[96:111], v[6:9], v[128:131], v[48:63]
	v_add_f32_e32 v2, v82, v14
	v_add_f32_e32 v2, v83, v2
	v_add_f32_e32 v14, v84, v2
	v_cvt_pk_bf16_f32 v177, v82, v83
	s_waitcnt lgkmcnt(1)
	v_mfma_f32_32x32x16_bf16 v[112:127], v[10:13], v[132:135], v[112:127]
	ds_read_b128 v[2:5], v0 offset:64
	ds_read_b128 v[6:9], v0 offset:6720
	v_add_f32_e32 v14, v85, v14
	v_add_f32_e32 v14, v86, v14
	v_add_f32_e32 v14, v87, v14
	v_cvt_pk_bf16_f32 v178, v84, v85
	v_cvt_pk_bf16_f32 v179, v86, v87
	s_waitcnt lgkmcnt(2)
	v_mfma_f32_32x32x16_bf16 v[96:111], v[202:205], v[132:135], v[96:111]
	v_add_f32_e32 v10, v88, v14
	v_add_f32_e32 v11, v89, v10
	v_cvt_pk_bf16_f32 v10, v88, v89
	s_waitcnt lgkmcnt(1)
	v_mfma_f32_32x32x16_bf16 v[112:127], v[2:5], v[136:139], v[112:127]
	ds_read_b128 v[80:83], v0 offset:96
	ds_read_b128 v[202:205], v0 offset:6752
	v_add_f32_e32 v11, v90, v11
	v_add_f32_e32 v11, v91, v11
	v_add_f32_e32 v12, v92, v11
	v_cvt_pk_bf16_f32 v11, v90, v91
	s_waitcnt lgkmcnt(2)
	v_mfma_f32_32x32x16_bf16 v[96:111], v[6:9], v[136:139], v[96:111]
	v_add_f32_e32 v2, v93, v12
	v_add_f32_e32 v2, v94, v2
	v_add_f32_e32 v14, v95, v2
	v_cvt_pk_bf16_f32 v12, v92, v93
	v_cvt_pk_bf16_f32 v13, v94, v95
	s_waitcnt lgkmcnt(1)
	v_mfma_f32_32x32x16_bf16 v[112:127], v[80:83], v[140:143], v[112:127]
	ds_read_b128 v[2:5], v0 offset:128
	ds_read_b128 v[206:209], v0 offset:6784
	v_add_f32_e32 v6, v16, v14
	v_add_f32_e32 v7, v17, v6
	v_cvt_pk_bf16_f32 v6, v16, v17
	s_waitcnt lgkmcnt(2)
	v_mfma_f32_32x32x16_bf16 v[96:111], v[202:205], v[140:143], v[96:111]
	v_add_f32_e32 v7, v18, v7
	v_add_f32_e32 v7, v19, v7
	v_add_f32_e32 v8, v20, v7
	v_cvt_pk_bf16_f32 v7, v18, v19
	s_waitcnt lgkmcnt(1)
	v_mfma_f32_32x32x16_bf16 v[112:127], v[2:5], v[144:147], v[112:127]
	ds_read_b128 v[14:17], v0 offset:160
	ds_read_b128 v[80:83], v0 offset:6816
	v_add_f32_e32 v0, v21, v8
	v_add_f32_e32 v0, v22, v0
	v_add_f32_e32 v0, v23, v0
	v_cvt_pk_bf16_f32 v8, v20, v21
	v_cvt_pk_bf16_f32 v9, v22, v23
	s_waitcnt lgkmcnt(2)
	v_mfma_f32_32x32x16_bf16 v[96:111], v[206:209], v[144:147], v[96:111]
	v_add_f32_e32 v0, v24, v0
	v_add_f32_e32 v0, v25, v0
	v_cvt_pk_bf16_f32 v2, v24, v25
	s_waitcnt lgkmcnt(1)
	v_mfma_f32_32x32x16_bf16 v[112:127], v[14:17], v[148:151], v[112:127]
	v_add_f32_e32 v0, v26, v0
	v_add_f32_e32 v0, v27, v0
	v_add_f32_e32 v0, v28, v0
	v_cvt_pk_bf16_f32 v3, v26, v27
	s_waitcnt lgkmcnt(0)
	v_mfma_f32_32x32x16_bf16 v[96:111], v[80:83], v[148:151], v[96:111]
	v_add_f32_e32 v0, v29, v0
	v_add_f32_e32 v0, v30, v0
	v_add_f32_e32 v0, v31, v0
	v_cvt_pk_bf16_f32 v4, v28, v29
	v_cvt_pk_bf16_f32 v5, v30, v31
	s_mul_i32 s4, s69, 0x2400
	v_add_u32_e32 v206, s4, v200
	ds_read_b128 v[16:19], v206 offset:53248
	ds_read_b128 v[202:205], v206 offset:57856
	s_cmp_ge_i32 s70, s65
	v_add_f32_e32 v201, v201, v0
	s_cbranch_scc1 .LBB0_693
	s_cmp_le_i32 s68, s63
	s_cbranch_scc0 .Latt_mask1
